# attention: sample items moved to 16 workgroups of every XCD and the 4th sequence's q-tile pairs made uneven (59/67) so per-workgroup tile counts match
# speedup vs baseline: 1.0524x; 1.0030x over previous
.LBB0_45:
	s_or_b64 exec, exec, s[6:7]
	s_barrier
	s_load_dword s0, s[94:95], 0xe0
	s_lshl_b32 s19, s2, 3
	s_lshl_b32 s56, s42, 3
	s_mul_i32 s81, s43, s42
	s_cmpk_lt_i32 s2, 0x810
	s_waitcnt lgkmcnt(0)
	s_mul_i32 s81, s81, s0
	s_cselect_b64 s[0:1], -1, 0
	s_ashr_i32 s3, s2, 31
	v_writelane_b32 v252, s0, 0
	s_ashr_i32 s43, s42, 31
	s_and_b32 s6, s42, 7
	v_writelane_b32 v252, s1, 1
	s_lshr_b32 s0, s3, 29
	s_add_i32 s0, s2, s0
	s_ashr_i32 s10, s0, 3
	s_and_b32 s0, s0, -8
	s_sub_i32 s11, s2, s0
	s_and_b32 s0, s2, 7
	s_ashr_i32 s1, s42, 3
	s_mul_i32 s0, s1, s0
	s_lshr_b32 s1, s2, 3
	s_add_i32 s7, s0, s1
	s_cmpk_lg_i32 s42, 0x100
	s_cselect_b64 s[0:1], -1, 0
	s_add_i32 s12, s42, 0x87f
	v_writelane_b32 v252, s0, 2
	s_cmpk_lt_i32 s2, 0x1080
	s_mov_b32 s73, 0
	v_writelane_b32 v252, s1, 3
	s_cselect_b64 s[0:1], -1, 0
	v_writelane_b32 v252, s0, 4
	s_lshr_b32 s13, s2, 7
	v_mov_b32_e32 v173, 0
	v_writelane_b32 v252, s1, 5
	s_and_b32 s0, s2, 0x7f
	s_and_b32 s1, s19, 0xffffe000
	s_lshl_b32 s4, s0, 6
	s_or_b32 s14, s1, s4
	s_cmp_lg_u32 s0, 0
	s_cselect_b64 s[0:1], -1, 0
	s_lshl_b32 s4, s2, 1
	s_and_b32 s4, s4, 0x7ffffff0
	s_add_i32 s15, s4, 0x6000
	s_cmpk_lt_i32 s2, 0xa0
	s_cselect_b64 s[4:5], -1, 0
	s_cmpk_lt_i32 s42, 0xc0
	v_writelane_b32 v252, s4, 6
	s_cselect_b64 s[8:9], -1, 0
	s_add_i32 s72, s2, 0xffffffe0
	v_writelane_b32 v252, s5, 7
	v_writelane_b32 v252, s8, 8
	s_or_b64 s[4:5], s[4:5], s[8:9]
	s_movk_i32 s33, 0xc0
	v_writelane_b32 v252, s9, 9
	v_writelane_b32 v252, s4, 10
	s_lshl_b64 s[8:9], s[72:73], 9
	s_mul_hi_i32 s85, s42, 0x16000
	v_writelane_b32 v252, s5, 11
	s_lshl_b64 s[4:5], s[2:3], 9
	v_writelane_b32 v252, s4, 12
	s_mul_i32 s84, s42, 0x16000
	s_movk_i32 s87, 0x4040
	v_writelane_b32 v252, s5, 13
	s_lshl_b64 s[4:5], s[42:43], 9
	v_writelane_b32 v252, s4, 14
	s_movk_i32 s92, 0x7fff
	s_movk_i32 s72, 0x300
	v_writelane_b32 v252, s5, 15
	s_add_i32 s4, s42, 0xffffffe0
	v_writelane_b32 v252, s8, 16
	s_mov_b32 s5, s73
	s_lshl_b64 s[4:5], s[4:5], 9
	v_writelane_b32 v252, s9, 17
	v_writelane_b32 v252, s4, 18
	s_cmpk_lt_i32 s2, 0x204
	v_mov_b32_e32 v216, 0x358637bd
	v_writelane_b32 v252, s5, 19
	s_cselect_b64 s[4:5], -1, 0
	v_writelane_b32 v252, s4, 20
	s_movk_i32 s86, 0x3000
	v_mov_b32_e32 v217, 0x1000
	v_writelane_b32 v252, s5, 21
	s_lshl_b32 s4, s11, 6
	s_or_b32 s4, s4, 4
	s_cmp_lt_i32 s11, 0
	s_movk_i32 s5, 0x103
	s_cselect_b32 s5, s5, 0x102
	s_mul_i32 s5, s11, s5
	s_add_i32 s5, s5, s10
	s_ashr_i32 s8, s5, 31
	s_lshr_b32 s8, s8, 25
	s_add_i32 s8, s5, s8
	s_ashr_i32 s9, s8, 7
	s_lshl_b32 s16, s9, 3
	s_sub_i32 s9, 0x81, s16
	s_and_b32 s8, s8, 0xffffff80
	s_min_u32 s17, s9, 8
	s_sub_i32 s18, s5, s8
	s_cmp_eq_u32 s6, 0
	s_cselect_b32 s6, s7, s2
	s_and_b32 s7, s6, 31
	s_cmp_lt_u32 s7, 16
	s_cselect_b64 s[8:9], -1, 0
	v_writelane_b32 v252, s8, 22
	s_lshr_b32 s8, s6, 5
	s_lshl_b32 s8, s8, 4
	s_add_i32 s8, s8, s7
	s_add_i32 s7, s8, 0x800
	v_cvt_f32_ubyte0_e32 v1, s17
	v_writelane_b32 v252, s9, 23
	v_writelane_b32 v252, s7, 24
	s_and_b32 s7, s6, 31
	v_writelane_b32 v252, s6, 25
	s_ashr_i32 s6, s6, 3
	s_and_b32 s6, s6, -4
	v_writelane_b32 v252, s6, 26
	s_xor_b32 s6, s7, 63
	v_writelane_b32 v252, s7, 27
	s_cmpk_lt_i32 s2, 0x1000
	v_writelane_b32 v252, s6, 28
	s_cselect_b64 s[6:7], -1, 0
	s_and_b64 s[8:9], s[6:7], exec
	s_cselect_b32 s8, 64, 16
	v_writelane_b32 v252, s8, 29
	s_cselect_b32 s8, s14, s15
	v_writelane_b32 v252, s8, 30
	s_cselect_b32 s8, s13, s2
	s_lshl_b32 s8, s8, 7
	s_and_b32 s8, s8, 0x380
	s_cmp_lt_i32 s11, 4
	s_mulk_i32 s11, 0x41
	s_cselect_b32 s4, s11, s4
	v_cvt_f32_i32_e32 v0, s18
	v_rcp_iflag_f32_e32 v2, v1
	s_add_i32 s4, s4, s10
	v_writelane_b32 v252, s8, 31
	s_ashr_i32 s8, s4, 31
	s_lshr_b32 s8, s8, 27
	s_add_i32 s8, s4, s8
	v_mul_f32_e32 v2, v0, v2
	s_ashr_i32 s9, s8, 5
	s_and_b64 s[0:1], s[0:1], s[6:7]
	v_trunc_f32_e32 v2, v2
	s_lshl_b32 s9, s9, 3
	v_writelane_b32 v252, s0, 32
	v_fma_f32 v0, -v2, v1, v0
	v_cvt_i32_f32_e32 v2, v2
	s_sub_i32 s10, 0x81, s9
	s_andn2_b32 s8, s8, 31
	v_writelane_b32 v252, s1, 33
	s_ashr_i32 s0, s18, 30
	s_min_u32 s10, s10, 8
	s_sub_i32 s4, s4, s8
	s_or_b32 s6, s0, 1
	v_cmp_ge_f32_e64 s[0:1], |v0|, v1
	s_and_b64 s[0:1], s[0:1], exec
	s_cselect_b32 s0, s6, 0
	v_readfirstlane_b32 s1, v2
	s_add_i32 s0, s1, s0
	s_abs_i32 s1, s42
	v_cvt_f32_u32_e32 v0, s1
	s_sub_i32 s7, 0, s1
	s_sext_i32_i8 s6, s0
	s_mul_i32 s0, s0, s17
	v_rcp_iflag_f32_e32 v0, v0
	v_writelane_b32 v252, s6, 34
	s_sub_i32 s0, s18, s0
	s_abs_i32 s6, s12
	v_mul_f32_e32 v0, 0x4f7ffffe, v0
	v_cvt_u32_f32_e32 v0, v0
	s_sext_i32_i8 s0, s0
	s_add_i32 s0, s16, s0
	v_writelane_b32 v252, s0, 35
	v_readfirstlane_b32 s8, v0
	s_mul_i32 s7, s7, s8
	s_mul_hi_u32 s7, s8, s7
	s_add_i32 s8, s8, s7
	s_mul_hi_u32 s7, s6, s8
	s_mul_i32 s8, s7, s1
	s_xor_b32 s0, s12, s42
	s_sub_i32 s6, s6, s8
	s_ashr_i32 s0, s0, 31
	s_add_i32 s8, s7, 1
	s_sub_i32 s11, s6, s1
	v_cvt_f32_ubyte0_e32 v1, s10
	s_cmp_ge_u32 s6, s1
	v_cvt_f32_i32_e32 v0, s4
	v_rcp_iflag_f32_e32 v2, v1
	s_cselect_b32 s7, s8, s7
	s_cselect_b32 s6, s11, s6
	s_add_i32 s8, s7, 1
	s_cmp_ge_u32 s6, s1
	s_cselect_b32 s1, s8, s7
	v_mul_f32_e32 v2, v0, v2
	s_xor_b32 s1, s1, s0
	v_trunc_f32_e32 v2, v2
	s_sub_i32 s0, s1, s0
	v_fma_f32 v0, -v2, v1, v0
	v_cvt_i32_f32_e32 v2, v2
	v_writelane_b32 v252, s0, 36
	s_ashr_i32 s0, s4, 30
	s_or_b32 s6, s0, 1
	v_cmp_ge_f32_e64 s[0:1], |v0|, v1
	s_and_b64 s[0:1], s[0:1], exec
	s_cselect_b32 s0, s6, 0
	v_readfirstlane_b32 s1, v2
	s_add_i32 s0, s1, s0
	s_sext_i32_i8 s1, s0
	v_writelane_b32 v252, s1, 37
	s_mul_i32 s1, s0, s10
	s_sub_i32 s1, s4, s1
	s_sext_i32_i8 s1, s1
	s_add_i32 s6, s9, s1
	s_movk_i32 s5, 0x80
	s_mov_b32 s4, s6
	s_ashr_i32 s7, s6, 31
	v_writelane_b32 v252, s4, 38
	s_lshl_b64 s[6:7], s[6:7], 19
	s_bfe_i64 s[0:1], s[0:1], 0x80000
	v_writelane_b32 v252, s5, 39
	v_writelane_b32 v252, s6, 40
	s_lshl_b64 s[0:1], s[0:1], 19
	s_ashr_i32 s57, s56, 31
	v_writelane_b32 v252, s7, 41
	v_writelane_b32 v252, s0, 42
	s_lshl_b64 s[60:61], s[56:57], 11
	v_mbcnt_lo_u32_b32 v0, -1, 0
	v_writelane_b32 v252, s1, 43
	s_lshl_b64 s[0:1], s[56:57], 12
	v_writelane_b32 v252, s0, 44
	v_mov_b32_e32 v218, 0x2000
	v_mov_b32_e32 v219, 0x2cfc000
	v_writelane_b32 v252, s1, 45
	v_writelane_b32 v252, s19, 46
	s_add_i32 s0, s19, s56
	v_writelane_b32 v252, s0, 47
	s_add_i32 s0, s2, s42
	s_lshl_b32 s1, s0, 3
	v_writelane_b32 v252, s1, 48
	s_lshl_b32 s0, s0, 1
	v_writelane_b32 v252, s0, 49
	s_lshl_b32 s0, s42, 1
	v_writelane_b32 v252, s0, 50
	s_lshl_b64 s[0:1], s[2:3], 2
	s_add_u32 s0, s0, 0x2cf5000
	s_addc_u32 s1, s1, 0
	v_writelane_b32 v252, s0, 51
	s_lshl_b64 s[6:7], s[42:43], 2
	v_mov_b32_e32 v220, 1
	v_writelane_b32 v252, s1, 52
	s_mul_hi_i32 s1, s2, 0x16000
	s_mul_i32 s0, s2, 0x16000
	v_writelane_b32 v252, s0, 53
	v_mov_b32_e32 v221, 0x3f4ccccd
	v_mbcnt_hi_u32_b32 v215, -1, v0
	v_writelane_b32 v252, s1, 54
	s_add_i32 s0, 0, 0x20000
	v_writelane_b32 v252, s0, 55
	s_add_i32 s0, 0, 0x20004
	v_writelane_b32 v252, s0, 56
	s_add_i32 s0, 0, 0x4400
	v_writelane_b32 v252, s0, 57
	s_add_i32 s0, 0, 0xd000
	v_writelane_b32 v252, s0, 58
	v_writelane_b32 v252, s6, 59
	v_mov_b64_e32 v[174:175], 0x80f
	v_mov_b64_e32 v[176:177], 0x810
	v_writelane_b32 v252, s7, 60
	s_lshl_b64 s[6:7], s[56:57], 13
	v_writelane_b32 v252, s6, 61
	v_mov_b32_e32 v222, 0xffffe003
	v_mov_b32_e32 v223, 0x7f800000
	v_writelane_b32 v252, s7, 62
	v_writelane_b32 v252, s94, 63
	v_mov_b32_e32 v224, 0xff800000
	v_mov_b32_e32 v225, 0x41b17218
	v_writelane_b32 v251, s95, 0
	v_mov_b32_e32 v226, 0x3fb8aa3b
	v_mov_b32_e32 v227, 0xffffff00
	v_mov_b32_e32 v228, 0xffffff80
	v_mov_b32_e32 v246, v173
	v_mov_b32_e32 v247, v173
	v_mov_b32_e32 v248, v173
	v_mov_b32_e32 v249, v173
	v_mov_b64_e32 v[178:179], 0x203
	v_mov_b64_e32 v[180:181], 0x204
	s_movk_i32 s4, 0x60
	s_add_i32 s1, 0, 0x11800
	s_add_i32 s0, 0, 0x17d00
	s_movk_i32 s69, 0xf0
	s_movk_i32 s93, 0x70
	s_mov_b64 s[76:77], 0
	s_mov_b64 s[78:79], 0x80
	s_mov_b32 s80, 0x3e38aa3b
	v_writelane_b32 v251, s96, 1
	s_nop 1
	v_writelane_b32 v251, s97, 2
	s_branch .LBB0_48

.LBB0_490:
	s_andn2_b64 vcc, exec, s[26:27]
	v_readlane_b32 s58, v252, 24
	s_cbranch_vccnz .LBB0_492
	s_lshr_b32 s10, s35, 1
	v_readlane_b32 s11, v252, 26
	s_or_b32 s10, s10, s11
	s_bitcmp0_b32 s35, 0
	v_readlane_b32 s11, v252, 27
	v_readlane_b32 s26, v252, 28
	s_cselect_b32 s11, s26, s11
	s_cmp_lt_u32 s35, 6
	s_cbranch_scc1 .Latt_stdpair
	v_readlane_b32 s26, v252, 27
	s_nop 1
	s_and_b32 s27, s26, 3
	s_and_b32 s28, s26, 12
	s_lshl_b32 s28, s28, 1
	s_add_i32 s27, s27, s28
	s_cmp_lt_u32 s26, 16
	s_cselect_b32 s28, 59, 63
	s_cselect_b32 s29, 0, 4
	s_sub_i32 s28, s28, s27
	s_add_i32 s29, s29, s27
	s_bitcmp0_b32 s35, 0
	s_cselect_b32 s11, s28, s29
.Latt_stdpair:
	s_lshl_b32 s10, s10, 6
	s_or_b32 s58, s10, s11
	s_mov_b64 s[10:11], -1
